# dn_prep stage 1: six conv tasks unrolled and software-pipelined by one task (next task's projection loads issued before the current task's compute, alternate register set in v88..v114)
# speedup vs baseline: 1.0062x; 1.0036x over previous
; #define LAS __attribute__((address_space(3)))
; __device__ __forceinline__ float lo_bf(unsigned w) { return __uint_as_float(w << 16); }
; __device__ __forceinline__ float hi_bf(unsigned w) { return __uint_as_float(w & 0xffff0000u); }
; __device__ __forceinline__ unsigned pk2(float lo, float hi) { const f32x2_t v = {lo, hi}; const bf16x2_t b = __builtin_convertvector(v, bf16x2_t); return __builtin_bit_cast(unsigned, b); }
; __device__ __forceinline__ float silu_(float x) { return x * sigm(x); }
; __device__ __forceinline__ void dn_prep_item(const Args& a, LAS unsigned char* lds, int item, int tid, int wave, int lane, int& cwh, int next_item) {
;     ...
;     for (int r = 0; r < 6; ++r) { const int task = tid + NTHR * r, which = task >> 10, i = (task & 1023) >> 4, gq = task & 15;
;         const int col = 1024 + which * 512 + h * 128 + 8 * gq;
;         v4u xv[4];
; #pragma unroll
;         for (int jj = 0; jj < 4; ++jj) { const int pos = n * 64 + i - 3 + jj; xv[jj] = (v4u){0u, 0u, 0u, 0u};
;             if (pos >= 0) xv[jj] = *(const v4u*)(P + (size_t)(b * T + pos) * NIN + col); }
;         float o[8];
; #pragma unroll
;         for (int q = 0; q < 8; ++q) o[q] = 0.f;
; #pragma unroll
;         for (int jj = 0; jj < 4; ++jj) { const v4u v = xv[jj];
;             const f32x4 w0 = *(const LAS f32x4*)(cwl + (which * 4 + jj) * 128 + 8 * gq), w1 = *(const LAS f32x4*)(cwl + (which * 4 + jj) * 128 + 8 * gq + 4);
;             o[0] += w0[0] * lo_bf(v.x); o[1] += w0[1] * hi_bf(v.x); o[2] += w0[2] * lo_bf(v.y); o[3] += w0[3] * hi_bf(v.y);
;             o[4] += w1[0] * lo_bf(v.z); o[5] += w1[1] * hi_bf(v.z); o[6] += w1[2] * lo_bf(v.w); o[7] += w1[3] * hi_bf(v.w); }
;         float s = 0.f;
; #pragma unroll
;         for (int q = 0; q < 8; ++q) { o[q] = silu_(o[q]); s += o[q] * o[q]; }
;         s += __shfl_xor(s, 1); s += __shfl_xor(s, 2); s += __shfl_xor(s, 4); s += __shfl_xor(s, 8);
;         const float inv = which == 2 ? 1.0f : rsqrtf(s + EPS) * (which == 0 ? 0.08838834764831845f : 1.0f);
;         v4u w; w.x = pk2(o[0] * inv, o[1] * inv); w.y = pk2(o[2] * inv, o[3] * inv); w.z = pk2(o[4] * inv, o[5] * inv); w.w = pk2(o[6] * inv, o[7] * inv);
;         *(LAS v4u*)(lds + (which == 0 ? L_QS : which == 1 ? L_KH : L_V) + i * KS_ + 16 * gq) = w;
.LBB0_746:
	v_add_u32_e32 v0, 0, v220
	v_lshrrev_b32_e32 v43, 10, v41
	v_and_b32_e32 v42, 63, v0
	v_lshl_add_u32 v1, v43, 9, v36
	v_add_u32_e32 v0, s86, v42
	v_cmp_lt_i32_e32 vcc, -1, v0
	v_mov_b32_e32 v8, 0
	v_lshlrev_b32_e32 v56, 1, v1
	v_mov_b32_e32 v16, 0
	v_mov_b32_e32 v17, 0
	v_mov_b32_e32 v18, 0
	v_mov_b32_e32 v19, 0
	s_and_saveexec_b64 s[22:23], vcc
	v_add_u32_e32 v1, s41, v0
	v_mov_b64_e32 v[2:3], s[10:11]
	v_mad_u64_u32 v[2:3], vcc, v1, s25, v[2:3]
	v_lshl_add_u64 v[2:3], v[2:3], 0, v[56:57]
	global_load_dwordx4 v[16:19], v[2:3], off
.Ls1t0_748:
	s_or_b64 exec, exec, s[22:23]
	v_cmp_lt_i32_e32 vcc, -2, v0
	v_mov_b32_e32 v9, 0
	v_mov_b32_e32 v10, 0
	v_mov_b32_e32 v11, 0
	s_and_saveexec_b64 s[22:23], vcc
	v_add_u32_e32 v1, s42, v0
	v_mov_b64_e32 v[2:3], s[10:11]
	v_mad_u64_u32 v[2:3], vcc, v1, s25, v[2:3]
	v_lshl_add_u64 v[2:3], v[2:3], 0, v[56:57]
	global_load_dwordx4 v[8:11], v[2:3], off
.Ls1t0_750:
	s_or_b64 exec, exec, s[22:23]
	v_cmp_lt_i32_e32 vcc, -3, v0
	v_mov_b32_e32 v20, 0
	v_mov_b32_e32 v21, 0
	v_mov_b32_e32 v22, 0
	v_mov_b32_e32 v23, 0
	s_and_saveexec_b64 s[22:23], vcc
	v_add_u32_e32 v2, s43, v0
	v_mov_b64_e32 v[0:1], s[10:11]
	v_mad_u64_u32 v[0:1], vcc, v2, s25, v[0:1]
	v_lshl_add_u64 v[0:1], v[0:1], 0, v[56:57]
	global_load_dwordx4 v[20:23], v[0:1], off
.Ls1t0_752:
	s_or_b64 exec, exec, s[22:23]
	v_or_b32_e32 v2, s39, v42
	v_mov_b64_e32 v[0:1], s[10:11]
	v_mad_u64_u32 v[0:1], s[22:23], v2, s25, v[0:1]
	v_lshl_add_u64 v[0:1], v[0:1], 0, v[56:57]
	global_load_dwordx4 v[4:7], v[0:1], off
	v_add_u32_e32 v108, 0x200, v41
	v_add_u32_e32 v0, 0, v219
	v_lshrrev_b32_e32 v110, 10, v108
	v_and_b32_e32 v109, 63, v0
	v_lshl_add_u32 v1, v110, 9, v36
	v_add_u32_e32 v0, s86, v109
	v_mov_b32_e32 v92, 0
	v_cmp_lt_i32_e32 vcc, -1, v0
	v_lshlrev_b32_e32 v56, 1, v1
	v_mov_b32_e32 v100, 0
	v_mov_b32_e32 v101, 0
	v_mov_b32_e32 v102, 0
	v_mov_b32_e32 v103, 0
	s_and_saveexec_b64 s[22:23], vcc
	v_add_u32_e32 v1, s41, v0
	v_mov_b64_e32 v[2:3], s[10:11]
	v_mad_u64_u32 v[2:3], vcc, v1, s25, v[2:3]
	v_lshl_add_u64 v[2:3], v[2:3], 0, v[56:57]
	global_load_dwordx4 v[100:103], v[2:3], off
.Ls1t1_756:
	s_or_b64 exec, exec, s[22:23]
	v_cmp_lt_i32_e32 vcc, -2, v0
	v_mov_b32_e32 v93, 0
	v_mov_b32_e32 v94, 0
	v_mov_b32_e32 v95, 0
	s_and_saveexec_b64 s[22:23], vcc
	v_add_u32_e32 v1, s42, v0
	v_mov_b64_e32 v[2:3], s[10:11]
	v_mad_u64_u32 v[2:3], vcc, v1, s25, v[2:3]
	v_lshl_add_u64 v[2:3], v[2:3], 0, v[56:57]
	global_load_dwordx4 v[92:95], v[2:3], off
.Ls1t1_758:
	s_or_b64 exec, exec, s[22:23]
	v_cmp_lt_i32_e32 vcc, -3, v0
	v_mov_b32_e32 v104, 0
	v_mov_b32_e32 v105, 0
	v_mov_b32_e32 v106, 0
	v_mov_b32_e32 v107, 0
	s_and_saveexec_b64 s[22:23], vcc
	v_add_u32_e32 v2, s43, v0
	v_mov_b64_e32 v[0:1], s[10:11]
	v_mad_u64_u32 v[0:1], vcc, v2, s25, v[0:1]
	v_lshl_add_u64 v[0:1], v[0:1], 0, v[56:57]
	global_load_dwordx4 v[104:107], v[0:1], off
; #define LAS __attribute__((address_space(3)))
; __device__ __forceinline__ float lo_bf(unsigned w) { return __uint_as_float(w << 16); }
; __device__ __forceinline__ float hi_bf(unsigned w) { return __uint_as_float(w & 0xffff0000u); }
; __device__ __forceinline__ unsigned pk2(float lo, float hi) { const f32x2_t v = {lo, hi}; const bf16x2_t b = __builtin_convertvector(v, bf16x2_t); return __builtin_bit_cast(unsigned, b); }
; __device__ __forceinline__ float silu_(float x) { return x * sigm(x); }
; __device__ __forceinline__ void dn_prep_item(const Args& a, LAS unsigned char* lds, int item, int tid, int wave, int lane, int& cwh, int next_item) {
;     ...
;     for (int r = 0; r < 6; ++r) { const int task = tid + NTHR * r, which = task >> 10, i = (task & 1023) >> 4, gq = task & 15;
;         const int col = 1024 + which * 512 + h * 128 + 8 * gq;
;         v4u xv[4];
; #pragma unroll
;         for (int jj = 0; jj < 4; ++jj) { const int pos = n * 64 + i - 3 + jj; xv[jj] = (v4u){0u, 0u, 0u, 0u};
;             if (pos >= 0) xv[jj] = *(const v4u*)(P + (size_t)(b * T + pos) * NIN + col); }
;         float o[8];
; #pragma unroll
;         for (int q = 0; q < 8; ++q) o[q] = 0.f;
; #pragma unroll
;         for (int jj = 0; jj < 4; ++jj) { const v4u v = xv[jj];
;             const f32x4 w0 = *(const LAS f32x4*)(cwl + (which * 4 + jj) * 128 + 8 * gq), w1 = *(const LAS f32x4*)(cwl + (which * 4 + jj) * 128 + 8 * gq + 4);
;             o[0] += w0[0] * lo_bf(v.x); o[1] += w0[1] * hi_bf(v.x); o[2] += w0[2] * lo_bf(v.y); o[3] += w0[3] * hi_bf(v.y);
;             o[4] += w1[0] * lo_bf(v.z); o[5] += w1[1] * hi_bf(v.z); o[6] += w1[2] * lo_bf(v.w); o[7] += w1[3] * hi_bf(v.w); }
;         float s = 0.f;
; #pragma unroll
;         for (int q = 0; q < 8; ++q) { o[q] = silu_(o[q]); s += o[q] * o[q]; }
;         s += __shfl_xor(s, 1); s += __shfl_xor(s, 2); s += __shfl_xor(s, 4); s += __shfl_xor(s, 8);
;         const float inv = which == 2 ? 1.0f : rsqrtf(s + EPS) * (which == 0 ? 0.08838834764831845f : 1.0f);
;         v4u w; w.x = pk2(o[0] * inv, o[1] * inv); w.y = pk2(o[2] * inv, o[3] * inv); w.z = pk2(o[4] * inv, o[5] * inv); w.w = pk2(o[6] * inv, o[7] * inv);
;         *(LAS v4u*)(lds + (which == 0 ? L_QS : which == 1 ? L_KH : L_V) + i * KS_ + 16 * gq) = w;
.Ls1t1_760:
	s_or_b64 exec, exec, s[22:23]
	v_or_b32_e32 v2, s39, v109
	v_mov_b64_e32 v[0:1], s[10:11]
	v_mad_u64_u32 v[0:1], s[22:23], v2, s25, v[0:1]
	v_lshl_add_u64 v[0:1], v[0:1], 0, v[56:57]
	global_load_dwordx4 v[88:91], v[0:1], off
	v_lshl_add_u32 v0, v43, 11, v150
	ds_read_b128 v[44:47], v0
	ds_read_b128 v[28:31], v0 offset:16
	ds_read_b128 v[72:75], v0 offset:512
	ds_read_b128 v[24:27], v0 offset:528
	ds_read_b128 v[76:79], v0 offset:1024
	ds_read_b128 v[12:15], v0 offset:1040
	ds_read_b128 v[80:83], v0 offset:1536
	ds_read_b128 v[0:3], v0 offset:1552
	s_waitcnt vmcnt(7)
	v_lshlrev_b32_e32 v32, 16, v16
	v_and_b32_e32 v33, 0xffff0000, v16
	s_waitcnt lgkmcnt(0)
	v_pk_fma_f32 v[32:33], v[44:45], v[32:33], 0 op_sel_hi:[1,1,0]
	s_waitcnt vmcnt(6)
	v_lshlrev_b32_e32 v34, 16, v8
	v_and_b32_e32 v35, 0xffff0000, v8
	v_pk_fma_f32 v[32:33], v[72:73], v[34:35], v[32:33]
	s_waitcnt vmcnt(5)
	v_lshlrev_b32_e32 v34, 16, v20
	v_and_b32_e32 v35, 0xffff0000, v20
	v_pk_fma_f32 v[32:33], v[76:77], v[34:35], v[32:33]
	v_lshlrev_b32_e32 v16, 16, v17
	v_and_b32_e32 v17, 0xffff0000, v17
	v_pk_fma_f32 v[16:17], v[46:47], v[16:17], 0 op_sel_hi:[1,1,0]
	v_lshlrev_b32_e32 v20, 16, v18
	v_cmp_ne_u32_e32 vcc, 2, v43
	s_waitcnt vmcnt(4)
	v_lshlrev_b32_e32 v34, 16, v4
	v_and_b32_e32 v35, 0xffff0000, v4
	v_pk_fma_f32 v[32:33], v[80:81], v[34:35], v[32:33]
	s_nop 0
	v_mul_f32_e32 v4, 0xbfb8aa3b, v32
	v_exp_f32_e32 v8, v4
	v_mov_b32_e32 v4, 1.0
	v_add_f32_e32 v8, 1.0, v8
	v_rcp_f32_e32 v34, v8
	v_mul_f32_e32 v8, 0xbfb8aa3b, v33
	v_exp_f32_e32 v8, v8
	s_nop 0
	v_add_f32_e32 v8, 1.0, v8
	v_rcp_f32_e32 v35, v8
	v_lshlrev_b32_e32 v8, 16, v9
	v_and_b32_e32 v9, 0xffff0000, v9
	v_pk_fma_f32 v[8:9], v[74:75], v[8:9], v[16:17]
	v_lshlrev_b32_e32 v16, 16, v21
	v_and_b32_e32 v17, 0xffff0000, v21
	v_pk_fma_f32 v[8:9], v[78:79], v[16:17], v[8:9]
	v_lshlrev_b32_e32 v16, 16, v5
	v_and_b32_e32 v17, 0xffff0000, v5
	v_pk_fma_f32 v[8:9], v[82:83], v[16:17], v[8:9]
	v_and_b32_e32 v21, 0xffff0000, v18
	v_mul_f32_e32 v5, 0xbfb8aa3b, v8
	v_exp_f32_e32 v5, v5
	v_pk_fma_f32 v[20:21], v[28:29], v[20:21], 0 op_sel_hi:[1,1,0]
	v_lshlrev_b32_e32 v28, 16, v10
	v_and_b32_e32 v29, 0xffff0000, v10
	v_add_f32_e32 v5, 1.0, v5
	v_rcp_f32_e32 v16, v5
	v_mul_f32_e32 v5, 0xbfb8aa3b, v9
	v_exp_f32_e32 v5, v5
	v_pk_fma_f32 v[20:21], v[24:25], v[28:29], v[20:21]
	v_lshlrev_b32_e32 v24, 16, v22
	v_and_b32_e32 v25, 0xffff0000, v22
	v_pk_fma_f32 v[12:13], v[12:13], v[24:25], v[20:21]
	v_lshlrev_b32_e32 v20, 16, v6
	v_and_b32_e32 v21, 0xffff0000, v6
	v_add_f32_e32 v5, 1.0, v5
	v_pk_fma_f32 v[0:1], v[0:1], v[20:21], v[12:13]
	v_rcp_f32_e32 v17, v5
	v_mul_f32_e32 v5, 0xbfb8aa3b, v0
	v_exp_f32_e32 v5, v5
	v_lshlrev_b32_e32 v18, 16, v19
	v_and_b32_e32 v19, 0xffff0000, v19
	v_pk_fma_f32 v[18:19], v[30:31], v[18:19], 0 op_sel_hi:[1,1,0]
	v_add_f32_e32 v5, 1.0, v5
	v_rcp_f32_e32 v12, v5
	v_mul_f32_e32 v5, 0xbfb8aa3b, v1
	v_exp_f32_e32 v5, v5
	v_lshlrev_b32_e32 v10, 16, v11
	v_and_b32_e32 v11, 0xffff0000, v11
	v_pk_fma_f32 v[10:11], v[26:27], v[10:11], v[18:19]
	v_lshlrev_b32_e32 v18, 16, v23
	v_and_b32_e32 v19, 0xffff0000, v23
	v_pk_fma_f32 v[10:11], v[14:15], v[18:19], v[10:11]
	v_lshlrev_b32_e32 v6, 16, v7
	v_and_b32_e32 v7, 0xffff0000, v7
	v_add_f32_e32 v5, 1.0, v5
	v_pk_fma_f32 v[2:3], v[2:3], v[6:7], v[10:11]
	v_rcp_f32_e32 v13, v5
	v_mul_f32_e32 v5, 0xbfb8aa3b, v2
	v_exp_f32_e32 v5, v5
	v_pk_mul_f32 v[32:33], v[32:33], v[34:35]
	v_pk_mul_f32 v[8:9], v[8:9], v[16:17]
	v_pk_mul_f32 v[34:35], v[32:33], v[32:33]
	v_add_f32_e32 v5, 1.0, v5
	v_rcp_f32_e32 v6, v5
	v_mul_f32_e32 v5, 0xbfb8aa3b, v3
	v_exp_f32_e32 v5, v5
	v_pk_mul_f32 v[16:17], v[8:9], v[8:9]
	v_pk_mul_f32 v[0:1], v[0:1], v[12:13]
	v_add_f32_e32 v5, 1.0, v5
	v_rcp_f32_e32 v7, v5
	v_add_f32_e32 v5, v34, v35
	v_add_f32_e32 v5, v16, v5
	v_pk_mul_f32 v[12:13], v[0:1], v[0:1]
	v_add_f32_e32 v5, v17, v5
	v_pk_mul_f32 v[2:3], v[2:3], v[6:7]
	v_add_f32_e32 v5, v12, v5
	v_pk_mul_f32 v[6:7], v[2:3], v[2:3]
	v_add_f32_e32 v5, v13, v5
	v_add_f32_e32 v5, v6, v5
	v_add_f32_e32 v5, v7, v5
	ds_bpermute_b32 v6, v37, v5
	s_waitcnt lgkmcnt(0)
	v_add_f32_e32 v5, v5, v6
	ds_bpermute_b32 v6, v38, v5
	s_waitcnt lgkmcnt(0)
	v_add_f32_e32 v5, v5, v6
	ds_bpermute_b32 v6, v39, v5
	s_waitcnt lgkmcnt(0)
	v_add_f32_e32 v5, v5, v6
	ds_bpermute_b32 v6, v40, v5
	s_and_saveexec_b64 s[22:23], vcc
	s_cbranch_execz .Ls1t0_754
	s_waitcnt lgkmcnt(0)
	v_add_f32_e32 v4, v5, v6
	v_add_f32_e32 v4, 0x358637bd, v4
	v_mul_f32_e32 v5, 0x4b800000, v4
	v_cmp_gt_f32_e32 vcc, s34, v4
	s_nop 1
	v_cndmask_b32_e32 v4, v4, v5, vcc
	v_rsq_f32_e32 v4, v4
	s_nop 0
	v_mul_f32_e32 v5, 0x45800000, v4
	v_cndmask_b32_e32 v4, v4, v5, vcc
	v_cmp_gt_u32_e32 vcc, s30, v41
	s_nop 1
	v_cndmask_b32_e32 v5, 1.0, v231, vcc
	v_mul_f32_e32 v4, v5, v4
.Ls1t0_754:
	s_or_b64 exec, exec, s[22:23]
	v_pk_mul_f32 v[0:1], v[0:1], v[4:5] op_sel_hi:[1,0]
	v_cmp_eq_u32_e32 vcc, 1, v43
	v_cvt_pk_bf16_f32 v12, v0, v1
	v_pk_mul_f32 v[0:1], v[2:3], v[4:5] op_sel_hi:[1,0]
	s_waitcnt lgkmcnt(0)
	v_pk_mul_f32 v[6:7], v[32:33], v[4:5] op_sel_hi:[1,0]
	v_cvt_pk_bf16_f32 v13, v0, v1
	v_cndmask_b32_e64 v0, v188, 0, vcc
	v_cmp_lt_u32_e32 vcc, s31, v41
	v_cvt_pk_bf16_f32 v10, v6, v7
	v_pk_mul_f32 v[6:7], v[8:9], v[4:5] op_sel_hi:[1,0]
	v_cndmask_b32_e32 v0, v232, v0, vcc
	v_add_u32_e32 v0, 0, v0
	v_mul_u32_u24_e32 v1, 0x110, v42
	v_cvt_pk_bf16_f32 v11, v6, v7
	v_add3_u32 v0, v0, v1, v151
	ds_write_b128 v0, v[10:13]
	v_add_u32_e32 v0, 0x400, v41
	v_lshrrev_b32_e32 v43, 10, v0
	v_add_u32_e32 v0, 0, v218
	v_and_b32_e32 v42, 63, v0
	v_lshl_add_u32 v1, v43, 9, v36
	v_add_u32_e32 v0, s86, v42
	v_mov_b32_e32 v8, 0
	v_cmp_lt_i32_e32 vcc, -1, v0
	v_lshlrev_b32_e32 v56, 1, v1
	v_mov_b32_e32 v16, 0
	v_mov_b32_e32 v17, 0
	v_mov_b32_e32 v18, 0
	v_mov_b32_e32 v19, 0
	s_and_saveexec_b64 s[22:23], vcc
	v_add_u32_e32 v1, s41, v0
	v_mov_b64_e32 v[2:3], s[10:11]
	v_mad_u64_u32 v[2:3], vcc, v1, s25, v[2:3]
	v_lshl_add_u64 v[2:3], v[2:3], 0, v[56:57]
	global_load_dwordx4 v[16:19], v[2:3], off

; #define LAS __attribute__((address_space(3)))
; __device__ __forceinline__ float lo_bf(unsigned w) { return __uint_as_float(w << 16); }
; __device__ __forceinline__ float hi_bf(unsigned w) { return __uint_as_float(w & 0xffff0000u); }
; __device__ __forceinline__ unsigned pk2(float lo, float hi) { const f32x2_t v = {lo, hi}; const bf16x2_t b = __builtin_convertvector(v, bf16x2_t); return __builtin_bit_cast(unsigned, b); }
; __device__ __forceinline__ float silu_(float x) { return x * sigm(x); }
; __device__ __forceinline__ void dn_prep_item(const Args& a, LAS unsigned char* lds, int item, int tid, int wave, int lane, int& cwh, int next_item) {
;     ...
;     for (int r = 0; r < 6; ++r) { const int task = tid + NTHR * r, which = task >> 10, i = (task & 1023) >> 4, gq = task & 15;
;         const int col = 1024 + which * 512 + h * 128 + 8 * gq;
;         v4u xv[4];
; #pragma unroll
;         for (int jj = 0; jj < 4; ++jj) { const int pos = n * 64 + i - 3 + jj; xv[jj] = (v4u){0u, 0u, 0u, 0u};
;             if (pos >= 0) xv[jj] = *(const v4u*)(P + (size_t)(b * T + pos) * NIN + col); }
;         float o[8];
; #pragma unroll
;         for (int q = 0; q < 8; ++q) o[q] = 0.f;
; #pragma unroll
;         for (int jj = 0; jj < 4; ++jj) { const v4u v = xv[jj];
;             const f32x4 w0 = *(const LAS f32x4*)(cwl + (which * 4 + jj) * 128 + 8 * gq), w1 = *(const LAS f32x4*)(cwl + (which * 4 + jj) * 128 + 8 * gq + 4);
;             o[0] += w0[0] * lo_bf(v.x); o[1] += w0[1] * hi_bf(v.x); o[2] += w0[2] * lo_bf(v.y); o[3] += w0[3] * hi_bf(v.y);
;             o[4] += w1[0] * lo_bf(v.z); o[5] += w1[1] * hi_bf(v.z); o[6] += w1[2] * lo_bf(v.w); o[7] += w1[3] * hi_bf(v.w); }
;         float s = 0.f;
; #pragma unroll
;         for (int q = 0; q < 8; ++q) { o[q] = silu_(o[q]); s += o[q] * o[q]; }
;         s += __shfl_xor(s, 1); s += __shfl_xor(s, 2); s += __shfl_xor(s, 4); s += __shfl_xor(s, 8);
;         const float inv = which == 2 ? 1.0f : rsqrtf(s + EPS) * (which == 0 ? 0.08838834764831845f : 1.0f);
;         v4u w; w.x = pk2(o[0] * inv, o[1] * inv); w.y = pk2(o[2] * inv, o[3] * inv); w.z = pk2(o[4] * inv, o[5] * inv); w.w = pk2(o[6] * inv, o[7] * inv);
;         *(LAS v4u*)(lds + (which == 0 ? L_QS : which == 1 ? L_KH : L_V) + i * KS_ + 16 * gq) = w;
.Ls1t2_768:
	s_or_b64 exec, exec, s[22:23]
	v_or_b32_e32 v2, s39, v42
	v_mov_b64_e32 v[0:1], s[10:11]
	v_mad_u64_u32 v[0:1], s[22:23], v2, s25, v[0:1]
	v_lshl_add_u64 v[0:1], v[0:1], 0, v[56:57]
	global_load_dwordx4 v[4:7], v[0:1], off
	v_lshl_add_u32 v0, v110, 11, v150
	ds_read_b128 v[72:75], v0
	ds_read_b128 v[28:31], v0 offset:16
	ds_read_b128 v[76:79], v0 offset:512
	ds_read_b128 v[24:27], v0 offset:528
	ds_read_b128 v[80:83], v0 offset:1024
	ds_read_b128 v[96:99], v0 offset:1040
	ds_read_b128 v[84:87], v0 offset:1536
	ds_read_b128 v[0:3], v0 offset:1552
	s_waitcnt vmcnt(7)
	v_lshlrev_b32_e32 v32, 16, v100
	v_and_b32_e32 v33, 0xffff0000, v100
	s_waitcnt lgkmcnt(7)
	v_pk_fma_f32 v[32:33], v[72:73], v[32:33], 0 op_sel_hi:[1,1,0]
	s_waitcnt vmcnt(6)
	v_lshlrev_b32_e32 v34, 16, v92
	v_and_b32_e32 v35, 0xffff0000, v92
	s_waitcnt lgkmcnt(5)
	v_pk_fma_f32 v[32:33], v[76:77], v[34:35], v[32:33]
	s_waitcnt vmcnt(5)
	v_lshlrev_b32_e32 v34, 16, v104
	v_and_b32_e32 v35, 0xffff0000, v104
	s_waitcnt lgkmcnt(3)
	v_pk_fma_f32 v[32:33], v[80:81], v[34:35], v[32:33]
	v_lshlrev_b32_e32 v100, 16, v101
	v_and_b32_e32 v101, 0xffff0000, v101
	v_pk_fma_f32 v[100:101], v[74:75], v[100:101], 0 op_sel_hi:[1,1,0]
	v_lshlrev_b32_e32 v104, 16, v102
	v_cmp_ne_u32_e32 vcc, 2, v110
	s_waitcnt vmcnt(4)
	v_lshlrev_b32_e32 v34, 16, v88
	v_and_b32_e32 v35, 0xffff0000, v88
	s_waitcnt lgkmcnt(1)
	v_pk_fma_f32 v[32:33], v[84:85], v[34:35], v[32:33]
	s_nop 0
	v_mul_f32_e32 v88, 0xbfb8aa3b, v32
	v_exp_f32_e32 v92, v88
	v_mov_b32_e32 v88, 1.0
	v_add_f32_e32 v92, 1.0, v92
	v_rcp_f32_e32 v34, v92
	v_mul_f32_e32 v92, 0xbfb8aa3b, v33
	v_exp_f32_e32 v92, v92
	s_nop 0
	v_add_f32_e32 v92, 1.0, v92
	v_rcp_f32_e32 v35, v92
	v_lshlrev_b32_e32 v92, 16, v93
	v_and_b32_e32 v93, 0xffff0000, v93
	v_pk_fma_f32 v[92:93], v[78:79], v[92:93], v[100:101]
	v_lshlrev_b32_e32 v100, 16, v105
	v_and_b32_e32 v101, 0xffff0000, v105
	v_pk_fma_f32 v[92:93], v[82:83], v[100:101], v[92:93]
	v_lshlrev_b32_e32 v100, 16, v89
	v_and_b32_e32 v101, 0xffff0000, v89
	v_pk_fma_f32 v[92:93], v[86:87], v[100:101], v[92:93]
	v_and_b32_e32 v105, 0xffff0000, v102
	v_mul_f32_e32 v89, 0xbfb8aa3b, v92
	v_exp_f32_e32 v89, v89
	v_pk_fma_f32 v[104:105], v[28:29], v[104:105], 0 op_sel_hi:[1,1,0]
	v_lshlrev_b32_e32 v28, 16, v94
	v_and_b32_e32 v29, 0xffff0000, v94
	v_add_f32_e32 v89, 1.0, v89
	v_rcp_f32_e32 v100, v89
	v_mul_f32_e32 v89, 0xbfb8aa3b, v93
	v_exp_f32_e32 v89, v89
	v_pk_fma_f32 v[104:105], v[24:25], v[28:29], v[104:105]
	v_lshlrev_b32_e32 v24, 16, v106
	v_and_b32_e32 v25, 0xffff0000, v106
	v_pk_fma_f32 v[96:97], v[96:97], v[24:25], v[104:105]
	v_lshlrev_b32_e32 v104, 16, v90
	v_and_b32_e32 v105, 0xffff0000, v90
	v_add_f32_e32 v89, 1.0, v89
	s_waitcnt lgkmcnt(0)
	v_pk_fma_f32 v[0:1], v[0:1], v[104:105], v[96:97]
	v_rcp_f32_e32 v101, v89
	v_mul_f32_e32 v89, 0xbfb8aa3b, v0
	v_exp_f32_e32 v89, v89
	v_lshlrev_b32_e32 v102, 16, v103
	v_and_b32_e32 v103, 0xffff0000, v103
	v_pk_fma_f32 v[102:103], v[30:31], v[102:103], 0 op_sel_hi:[1,1,0]
	v_add_f32_e32 v89, 1.0, v89
	v_rcp_f32_e32 v96, v89
	v_mul_f32_e32 v89, 0xbfb8aa3b, v1
	v_exp_f32_e32 v89, v89
	v_lshlrev_b32_e32 v94, 16, v95
	v_and_b32_e32 v95, 0xffff0000, v95
	v_pk_fma_f32 v[94:95], v[26:27], v[94:95], v[102:103]
	v_lshlrev_b32_e32 v102, 16, v107
	v_and_b32_e32 v103, 0xffff0000, v107
	v_pk_fma_f32 v[94:95], v[98:99], v[102:103], v[94:95]
	v_lshlrev_b32_e32 v90, 16, v91
	v_and_b32_e32 v91, 0xffff0000, v91
	v_add_f32_e32 v89, 1.0, v89
	v_pk_fma_f32 v[2:3], v[2:3], v[90:91], v[94:95]
	v_rcp_f32_e32 v97, v89
	v_mul_f32_e32 v89, 0xbfb8aa3b, v2
	v_exp_f32_e32 v89, v89
	v_pk_mul_f32 v[32:33], v[32:33], v[34:35]
	v_pk_mul_f32 v[92:93], v[92:93], v[100:101]
	v_pk_mul_f32 v[34:35], v[32:33], v[32:33]
	v_add_f32_e32 v89, 1.0, v89
	v_rcp_f32_e32 v90, v89
	v_mul_f32_e32 v89, 0xbfb8aa3b, v3
	v_exp_f32_e32 v89, v89
	v_pk_mul_f32 v[100:101], v[92:93], v[92:93]
	v_pk_mul_f32 v[0:1], v[0:1], v[96:97]
	v_add_f32_e32 v89, 1.0, v89
	v_rcp_f32_e32 v91, v89
	v_add_f32_e32 v89, v34, v35
	v_add_f32_e32 v89, v100, v89
	v_pk_mul_f32 v[96:97], v[0:1], v[0:1]
	v_add_f32_e32 v89, v101, v89
	v_pk_mul_f32 v[2:3], v[2:3], v[90:91]
	v_add_f32_e32 v89, v96, v89
	v_pk_mul_f32 v[90:91], v[2:3], v[2:3]
	v_add_f32_e32 v89, v97, v89
	v_add_f32_e32 v89, v90, v89
	v_add_f32_e32 v89, v91, v89
	ds_bpermute_b32 v90, v37, v89
	s_waitcnt lgkmcnt(0)
	v_add_f32_e32 v89, v89, v90
	ds_bpermute_b32 v90, v38, v89
	s_waitcnt lgkmcnt(0)
	v_add_f32_e32 v89, v89, v90
	ds_bpermute_b32 v90, v39, v89
	s_waitcnt lgkmcnt(0)
	v_add_f32_e32 v89, v89, v90
	ds_bpermute_b32 v90, v40, v89
	s_and_saveexec_b64 s[22:23], vcc
	s_cbranch_execz .Ls1t1_762
	s_waitcnt lgkmcnt(0)
	v_add_f32_e32 v88, v89, v90
	v_add_f32_e32 v88, 0x358637bd, v88
	v_mul_f32_e32 v89, 0x4b800000, v88
	v_cmp_gt_f32_e32 vcc, s34, v88
	s_nop 1
	v_cndmask_b32_e32 v88, v88, v89, vcc
	v_rsq_f32_e32 v88, v88
	s_nop 0
	v_mul_f32_e32 v89, 0x45800000, v88
	v_cndmask_b32_e32 v88, v88, v89, vcc
	v_cmp_gt_u32_e32 vcc, s30, v108
	s_nop 1
	v_cndmask_b32_e32 v89, 1.0, v231, vcc
	v_mul_f32_e32 v88, v89, v88
.Ls1t1_762:
	s_or_b64 exec, exec, s[22:23]
	v_pk_mul_f32 v[0:1], v[0:1], v[88:89] op_sel_hi:[1,0]
	v_cmp_eq_u32_e32 vcc, 1, v110
	v_cvt_pk_bf16_f32 v96, v0, v1
	v_pk_mul_f32 v[0:1], v[2:3], v[88:89] op_sel_hi:[1,0]
	s_waitcnt lgkmcnt(0)
	v_pk_mul_f32 v[90:91], v[32:33], v[88:89] op_sel_hi:[1,0]
	v_cvt_pk_bf16_f32 v97, v0, v1
	v_cndmask_b32_e64 v0, v188, 0, vcc
	v_cmp_lt_u32_e32 vcc, s31, v108
	v_cvt_pk_bf16_f32 v94, v90, v91
	v_pk_mul_f32 v[90:91], v[92:93], v[88:89] op_sel_hi:[1,0]
	v_cndmask_b32_e32 v0, v232, v0, vcc
	v_add_u32_e32 v0, 0, v0
	v_mul_u32_u24_e32 v1, 0x110, v109
	v_cvt_pk_bf16_f32 v95, v90, v91
	v_add3_u32 v0, v0, v1, v151
	ds_write_b128 v0, v[94:97]
	v_add_u32_e32 v111, 0x600, v41
	v_add_u32_e32 v0, 0x60, v220
	v_lshrrev_b32_e32 v109, 10, v111
	v_and_b32_e32 v108, 63, v0
	v_lshl_add_u32 v1, v109, 9, v36
	v_add_u32_e32 v0, s86, v108
	v_cmp_lt_i32_e32 vcc, -1, v0
	v_mov_b32_e32 v92, 0
	v_lshlrev_b32_e32 v56, 1, v1
	v_mov_b32_e32 v100, 0
	v_mov_b32_e32 v101, 0
	v_mov_b32_e32 v102, 0
	v_mov_b32_e32 v103, 0
	s_and_saveexec_b64 s[22:23], vcc
	v_add_u32_e32 v1, s41, v0
	v_mov_b64_e32 v[2:3], s[10:11]
	v_mad_u64_u32 v[2:3], vcc, v1, s25, v[2:3]
	v_lshl_add_u64 v[2:3], v[2:3], 0, v[56:57]
	global_load_dwordx4 v[100:103], v[2:3], off

; #define LAS __attribute__((address_space(3)))
; __device__ __forceinline__ float lo_bf(unsigned w) { return __uint_as_float(w << 16); }
; __device__ __forceinline__ float hi_bf(unsigned w) { return __uint_as_float(w & 0xffff0000u); }
; __device__ __forceinline__ unsigned pk2(float lo, float hi) { const f32x2_t v = {lo, hi}; const bf16x2_t b = __builtin_convertvector(v, bf16x2_t); return __builtin_bit_cast(unsigned, b); }
; __device__ __forceinline__ float silu_(float x) { return x * sigm(x); }
; __device__ __forceinline__ void dn_prep_item(const Args& a, LAS unsigned char* lds, int item, int tid, int wave, int lane, int& cwh, int next_item) {
;     ...
;     for (int r = 0; r < 6; ++r) { const int task = tid + NTHR * r, which = task >> 10, i = (task & 1023) >> 4, gq = task & 15;
;         const int col = 1024 + which * 512 + h * 128 + 8 * gq;
;         v4u xv[4];
; #pragma unroll
;         for (int jj = 0; jj < 4; ++jj) { const int pos = n * 64 + i - 3 + jj; xv[jj] = (v4u){0u, 0u, 0u, 0u};
;             if (pos >= 0) xv[jj] = *(const v4u*)(P + (size_t)(b * T + pos) * NIN + col); }
;         float o[8];
; #pragma unroll
;         for (int q = 0; q < 8; ++q) o[q] = 0.f;
; #pragma unroll
;         for (int jj = 0; jj < 4; ++jj) { const v4u v = xv[jj];
;             const f32x4 w0 = *(const LAS f32x4*)(cwl + (which * 4 + jj) * 128 + 8 * gq), w1 = *(const LAS f32x4*)(cwl + (which * 4 + jj) * 128 + 8 * gq + 4);
;             o[0] += w0[0] * lo_bf(v.x); o[1] += w0[1] * hi_bf(v.x); o[2] += w0[2] * lo_bf(v.y); o[3] += w0[3] * hi_bf(v.y);
;             o[4] += w1[0] * lo_bf(v.z); o[5] += w1[1] * hi_bf(v.z); o[6] += w1[2] * lo_bf(v.w); o[7] += w1[3] * hi_bf(v.w); }
;         float s = 0.f;
; #pragma unroll
;         for (int q = 0; q < 8; ++q) { o[q] = silu_(o[q]); s += o[q] * o[q]; }
;         s += __shfl_xor(s, 1); s += __shfl_xor(s, 2); s += __shfl_xor(s, 4); s += __shfl_xor(s, 8);
;         const float inv = which == 2 ? 1.0f : rsqrtf(s + EPS) * (which == 0 ? 0.08838834764831845f : 1.0f);
;         v4u w; w.x = pk2(o[0] * inv, o[1] * inv); w.y = pk2(o[2] * inv, o[3] * inv); w.z = pk2(o[4] * inv, o[5] * inv); w.w = pk2(o[6] * inv, o[7] * inv);
;         *(LAS v4u*)(lds + (which == 0 ? L_QS : which == 1 ? L_KH : L_V) + i * KS_ + 16 * gq) = w;
.Ls1t3_752:
	s_or_b64 exec, exec, s[22:23]
	v_or_b32_e32 v2, s39, v108
	v_mov_b64_e32 v[0:1], s[10:11]
	v_mad_u64_u32 v[0:1], s[22:23], v2, s25, v[0:1]
	v_lshl_add_u64 v[0:1], v[0:1], 0, v[56:57]
	global_load_dwordx4 v[88:91], v[0:1], off
	v_lshl_add_u32 v0, v43, 11, v150
	ds_read_b128 v[44:47], v0
	ds_read_b128 v[28:31], v0 offset:16
	ds_read_b128 v[72:75], v0 offset:512
	ds_read_b128 v[24:27], v0 offset:528
	ds_read_b128 v[76:79], v0 offset:1024
	ds_read_b128 v[12:15], v0 offset:1040
	ds_read_b128 v[80:83], v0 offset:1536
	ds_read_b128 v[0:3], v0 offset:1552
	s_waitcnt vmcnt(7)
	v_lshlrev_b32_e32 v32, 16, v16
	v_and_b32_e32 v33, 0xffff0000, v16
	s_waitcnt lgkmcnt(7)
	v_pk_fma_f32 v[32:33], v[44:45], v[32:33], 0 op_sel_hi:[1,1,0]
	s_waitcnt vmcnt(6)
	v_lshlrev_b32_e32 v34, 16, v8
	v_and_b32_e32 v35, 0xffff0000, v8
	s_waitcnt lgkmcnt(5)
	v_pk_fma_f32 v[32:33], v[72:73], v[34:35], v[32:33]
	s_waitcnt vmcnt(5)
	v_lshlrev_b32_e32 v34, 16, v20
	v_and_b32_e32 v35, 0xffff0000, v20
	s_waitcnt lgkmcnt(3)
	v_pk_fma_f32 v[32:33], v[76:77], v[34:35], v[32:33]
	v_lshlrev_b32_e32 v16, 16, v17
	v_and_b32_e32 v17, 0xffff0000, v17
	v_pk_fma_f32 v[16:17], v[46:47], v[16:17], 0 op_sel_hi:[1,1,0]
	v_lshlrev_b32_e32 v20, 16, v18
	v_cmp_ne_u32_e32 vcc, 2, v43
	s_waitcnt vmcnt(4)
	v_lshlrev_b32_e32 v34, 16, v4
	v_and_b32_e32 v35, 0xffff0000, v4
	s_waitcnt lgkmcnt(1)
	v_pk_fma_f32 v[32:33], v[80:81], v[34:35], v[32:33]
	s_nop 0
	v_mul_f32_e32 v4, 0xbfb8aa3b, v32
	v_exp_f32_e32 v8, v4
	v_mov_b32_e32 v4, 1.0
	v_add_f32_e32 v8, 1.0, v8
	v_rcp_f32_e32 v34, v8
	v_mul_f32_e32 v8, 0xbfb8aa3b, v33
	v_exp_f32_e32 v8, v8
	s_nop 0
	v_add_f32_e32 v8, 1.0, v8
	v_rcp_f32_e32 v35, v8
	v_lshlrev_b32_e32 v8, 16, v9
	v_and_b32_e32 v9, 0xffff0000, v9
	v_pk_fma_f32 v[8:9], v[74:75], v[8:9], v[16:17]
	v_lshlrev_b32_e32 v16, 16, v21
	v_and_b32_e32 v17, 0xffff0000, v21
	v_pk_fma_f32 v[8:9], v[78:79], v[16:17], v[8:9]
	v_lshlrev_b32_e32 v16, 16, v5
	v_and_b32_e32 v17, 0xffff0000, v5
	v_pk_fma_f32 v[8:9], v[82:83], v[16:17], v[8:9]
	v_and_b32_e32 v21, 0xffff0000, v18
	v_mul_f32_e32 v5, 0xbfb8aa3b, v8
	v_exp_f32_e32 v5, v5
	v_pk_fma_f32 v[20:21], v[28:29], v[20:21], 0 op_sel_hi:[1,1,0]
	v_lshlrev_b32_e32 v28, 16, v10
	v_and_b32_e32 v29, 0xffff0000, v10
	v_add_f32_e32 v5, 1.0, v5
	v_rcp_f32_e32 v16, v5
	v_mul_f32_e32 v5, 0xbfb8aa3b, v9
	v_exp_f32_e32 v5, v5
	v_pk_fma_f32 v[20:21], v[24:25], v[28:29], v[20:21]
	v_lshlrev_b32_e32 v24, 16, v22
	v_and_b32_e32 v25, 0xffff0000, v22
	v_pk_fma_f32 v[12:13], v[12:13], v[24:25], v[20:21]
	v_lshlrev_b32_e32 v20, 16, v6
	v_and_b32_e32 v21, 0xffff0000, v6
	v_add_f32_e32 v5, 1.0, v5
	s_waitcnt lgkmcnt(0)
	v_pk_fma_f32 v[0:1], v[0:1], v[20:21], v[12:13]
	v_rcp_f32_e32 v17, v5
	v_mul_f32_e32 v5, 0xbfb8aa3b, v0
	v_exp_f32_e32 v5, v5
	v_lshlrev_b32_e32 v18, 16, v19
	v_and_b32_e32 v19, 0xffff0000, v19
	v_pk_fma_f32 v[18:19], v[30:31], v[18:19], 0 op_sel_hi:[1,1,0]
	v_add_f32_e32 v5, 1.0, v5
	v_rcp_f32_e32 v12, v5
	v_mul_f32_e32 v5, 0xbfb8aa3b, v1
	v_exp_f32_e32 v5, v5
	v_lshlrev_b32_e32 v10, 16, v11
	v_and_b32_e32 v11, 0xffff0000, v11
	v_pk_fma_f32 v[10:11], v[26:27], v[10:11], v[18:19]
	v_lshlrev_b32_e32 v18, 16, v23
	v_and_b32_e32 v19, 0xffff0000, v23
	v_pk_fma_f32 v[10:11], v[14:15], v[18:19], v[10:11]
	v_lshlrev_b32_e32 v6, 16, v7
	v_and_b32_e32 v7, 0xffff0000, v7
	v_add_f32_e32 v5, 1.0, v5
	v_pk_fma_f32 v[2:3], v[2:3], v[6:7], v[10:11]
	v_rcp_f32_e32 v13, v5
	v_mul_f32_e32 v5, 0xbfb8aa3b, v2
	v_exp_f32_e32 v5, v5
	v_pk_mul_f32 v[32:33], v[32:33], v[34:35]
	v_pk_mul_f32 v[8:9], v[8:9], v[16:17]
	v_pk_mul_f32 v[34:35], v[32:33], v[32:33]
	v_add_f32_e32 v5, 1.0, v5
	v_rcp_f32_e32 v6, v5
	v_mul_f32_e32 v5, 0xbfb8aa3b, v3
	v_exp_f32_e32 v5, v5
	v_pk_mul_f32 v[16:17], v[8:9], v[8:9]
	v_pk_mul_f32 v[0:1], v[0:1], v[12:13]
	v_add_f32_e32 v5, 1.0, v5
	v_rcp_f32_e32 v7, v5
	v_add_f32_e32 v5, v34, v35
	v_add_f32_e32 v5, v16, v5
	v_pk_mul_f32 v[12:13], v[0:1], v[0:1]
	v_add_f32_e32 v5, v17, v5
	v_pk_mul_f32 v[2:3], v[2:3], v[6:7]
	v_add_f32_e32 v5, v12, v5
	v_pk_mul_f32 v[6:7], v[2:3], v[2:3]
	v_add_f32_e32 v5, v13, v5
	v_add_f32_e32 v5, v6, v5
	v_add_f32_e32 v5, v7, v5
	ds_bpermute_b32 v6, v37, v5
	s_waitcnt lgkmcnt(0)
	v_add_f32_e32 v5, v5, v6
	ds_bpermute_b32 v6, v38, v5
	s_waitcnt lgkmcnt(0)
	v_add_f32_e32 v5, v5, v6
	ds_bpermute_b32 v6, v39, v5
	s_waitcnt lgkmcnt(0)
	v_add_f32_e32 v5, v5, v6
	ds_bpermute_b32 v6, v40, v5
	s_and_saveexec_b64 s[22:23], vcc
	s_cbranch_execz .Ls1t2_745
	s_waitcnt lgkmcnt(0)
	v_add_f32_e32 v4, v5, v6
	v_add_f32_e32 v4, 0x358637bd, v4
	v_mul_f32_e32 v5, 0x4b800000, v4
	v_cmp_gt_f32_e32 vcc, s34, v4
	s_nop 1
	v_cndmask_b32_e32 v4, v4, v5, vcc
	v_rsq_f32_e32 v4, v4
	s_nop 0
	v_mul_f32_e32 v5, 0x45800000, v4
	v_cndmask_b32_e32 v4, v4, v5, vcc
.Ls1t2_745:
	s_or_b64 exec, exec, s[22:23]
	s_waitcnt lgkmcnt(0)
	v_pk_mul_f32 v[6:7], v[32:33], v[4:5] op_sel_hi:[1,0]
	v_pk_mul_f32 v[8:9], v[8:9], v[4:5] op_sel_hi:[1,0]
	v_pk_mul_f32 v[0:1], v[0:1], v[4:5] op_sel_hi:[1,0]
	v_cvt_pk_bf16_f32 v6, v6, v7
	v_cvt_pk_bf16_f32 v7, v8, v9
	v_cvt_pk_bf16_f32 v8, v0, v1
	v_pk_mul_f32 v[0:1], v[2:3], v[4:5] op_sel_hi:[1,0]
	v_cmp_eq_u32_e32 vcc, 1, v43
	v_cvt_pk_bf16_f32 v9, v0, v1
	v_mul_u32_u24_e32 v1, 0x110, v42
	v_cndmask_b32_e64 v0, v188, 0, vcc
	v_add_u32_e32 v0, 0, v0
	v_add3_u32 v0, v0, v1, v151
	ds_write_b128 v0, v[6:9]
	v_add_u32_e32 v112, 0x200, v111
	v_add_u32_e32 v0, 0x60, v219
	v_lshrrev_b32_e32 v114, 10, v112
	v_and_b32_e32 v113, 63, v0
	v_lshl_add_u32 v1, v114, 9, v36
	v_add_u32_e32 v0, s86, v113
	v_mov_b32_e32 v8, 0
	v_cmp_lt_i32_e32 vcc, -1, v0
	v_lshlrev_b32_e32 v56, 1, v1
	v_mov_b32_e32 v16, 0
	v_mov_b32_e32 v17, 0
	v_mov_b32_e32 v18, 0
	v_mov_b32_e32 v19, 0
	s_and_saveexec_b64 s[22:23], vcc
	v_add_u32_e32 v1, s41, v0
	v_mov_b64_e32 v[2:3], s[10:11]
	v_mad_u64_u32 v[2:3], vcc, v1, s25, v[2:3]
	v_lshl_add_u64 v[2:3], v[2:3], 0, v[56:57]
	global_load_dwordx4 v[16:19], v[2:3], off

; #define LAS __attribute__((address_space(3)))
; __device__ __forceinline__ float lo_bf(unsigned w) { return __uint_as_float(w << 16); }
; __device__ __forceinline__ float hi_bf(unsigned w) { return __uint_as_float(w & 0xffff0000u); }
; __device__ __forceinline__ unsigned pk2(float lo, float hi) { const f32x2_t v = {lo, hi}; const bf16x2_t b = __builtin_convertvector(v, bf16x2_t); return __builtin_bit_cast(unsigned, b); }
; __device__ __forceinline__ float silu_(float x) { return x * sigm(x); }
; __device__ __forceinline__ void dn_prep_item(const Args& a, LAS unsigned char* lds, int item, int tid, int wave, int lane, int& cwh, int next_item) {
;     ...
;     for (int r = 0; r < 6; ++r) { const int task = tid + NTHR * r, which = task >> 10, i = (task & 1023) >> 4, gq = task & 15;
;         const int col = 1024 + which * 512 + h * 128 + 8 * gq;
;         v4u xv[4];
; #pragma unroll
;         for (int jj = 0; jj < 4; ++jj) { const int pos = n * 64 + i - 3 + jj; xv[jj] = (v4u){0u, 0u, 0u, 0u};
;             if (pos >= 0) xv[jj] = *(const v4u*)(P + (size_t)(b * T + pos) * NIN + col); }
;         float o[8];
; #pragma unroll
;         for (int q = 0; q < 8; ++q) o[q] = 0.f;
; #pragma unroll
;         for (int jj = 0; jj < 4; ++jj) { const v4u v = xv[jj];
;             const f32x4 w0 = *(const LAS f32x4*)(cwl + (which * 4 + jj) * 128 + 8 * gq), w1 = *(const LAS f32x4*)(cwl + (which * 4 + jj) * 128 + 8 * gq + 4);
;             o[0] += w0[0] * lo_bf(v.x); o[1] += w0[1] * hi_bf(v.x); o[2] += w0[2] * lo_bf(v.y); o[3] += w0[3] * hi_bf(v.y);
;             o[4] += w1[0] * lo_bf(v.z); o[5] += w1[1] * hi_bf(v.z); o[6] += w1[2] * lo_bf(v.w); o[7] += w1[3] * hi_bf(v.w); }
;         float s = 0.f;
; #pragma unroll
;         for (int q = 0; q < 8; ++q) { o[q] = silu_(o[q]); s += o[q] * o[q]; }
;         s += __shfl_xor(s, 1); s += __shfl_xor(s, 2); s += __shfl_xor(s, 4); s += __shfl_xor(s, 8);
;         const float inv = which == 2 ? 1.0f : rsqrtf(s + EPS) * (which == 0 ? 0.08838834764831845f : 1.0f);
;         v4u w; w.x = pk2(o[0] * inv, o[1] * inv); w.y = pk2(o[2] * inv, o[3] * inv); w.z = pk2(o[4] * inv, o[5] * inv); w.w = pk2(o[6] * inv, o[7] * inv);
;         *(LAS v4u*)(lds + (which == 0 ? L_QS : which == 1 ? L_KH : L_V) + i * KS_ + 16 * gq) = w;
.Ls1t4_760:
	s_or_b64 exec, exec, s[22:23]
	v_or_b32_e32 v2, s39, v113
	v_mov_b64_e32 v[0:1], s[10:11]
	v_mad_u64_u32 v[0:1], s[22:23], v2, s25, v[0:1]
	v_lshl_add_u64 v[0:1], v[0:1], 0, v[56:57]
	global_load_dwordx4 v[4:7], v[0:1], off
	v_lshl_add_u32 v0, v109, 11, v150
	ds_read_b128 v[44:47], v0
	ds_read_b128 v[28:31], v0 offset:16
	ds_read_b128 v[72:75], v0 offset:512
	ds_read_b128 v[24:27], v0 offset:528
	ds_read_b128 v[76:79], v0 offset:1024
	ds_read_b128 v[96:99], v0 offset:1040
	ds_read_b128 v[80:83], v0 offset:1536
	ds_read_b128 v[0:3], v0 offset:1552
	s_waitcnt vmcnt(7)
	v_lshlrev_b32_e32 v32, 16, v100
	v_and_b32_e32 v33, 0xffff0000, v100
	s_waitcnt lgkmcnt(0)
	v_pk_fma_f32 v[32:33], v[44:45], v[32:33], 0 op_sel_hi:[1,1,0]
	s_waitcnt vmcnt(6)
	v_lshlrev_b32_e32 v34, 16, v92
	v_and_b32_e32 v35, 0xffff0000, v92
	v_pk_fma_f32 v[32:33], v[72:73], v[34:35], v[32:33]
	s_waitcnt vmcnt(5)
	v_lshlrev_b32_e32 v34, 16, v104
	v_and_b32_e32 v35, 0xffff0000, v104
	v_pk_fma_f32 v[32:33], v[76:77], v[34:35], v[32:33]
	v_lshlrev_b32_e32 v100, 16, v101
	v_and_b32_e32 v101, 0xffff0000, v101
	v_pk_fma_f32 v[100:101], v[46:47], v[100:101], 0 op_sel_hi:[1,1,0]
	v_lshlrev_b32_e32 v104, 16, v102
	v_cmp_ne_u32_e32 vcc, 2, v109
	s_waitcnt vmcnt(4)
	v_lshlrev_b32_e32 v34, 16, v88
	v_and_b32_e32 v35, 0xffff0000, v88
	v_pk_fma_f32 v[32:33], v[80:81], v[34:35], v[32:33]
	s_nop 0
	v_mul_f32_e32 v88, 0xbfb8aa3b, v32
	v_exp_f32_e32 v92, v88
	v_mov_b32_e32 v88, 1.0
	v_add_f32_e32 v92, 1.0, v92
	v_rcp_f32_e32 v34, v92
	v_mul_f32_e32 v92, 0xbfb8aa3b, v33
	v_exp_f32_e32 v92, v92
	s_nop 0
	v_add_f32_e32 v92, 1.0, v92
	v_rcp_f32_e32 v35, v92
	v_lshlrev_b32_e32 v92, 16, v93
	v_and_b32_e32 v93, 0xffff0000, v93
	v_pk_fma_f32 v[92:93], v[74:75], v[92:93], v[100:101]
	v_lshlrev_b32_e32 v100, 16, v105
	v_and_b32_e32 v101, 0xffff0000, v105
	v_pk_fma_f32 v[92:93], v[78:79], v[100:101], v[92:93]
	v_lshlrev_b32_e32 v100, 16, v89
	v_and_b32_e32 v101, 0xffff0000, v89
	v_pk_fma_f32 v[92:93], v[82:83], v[100:101], v[92:93]
	v_and_b32_e32 v105, 0xffff0000, v102
	v_mul_f32_e32 v89, 0xbfb8aa3b, v92
	v_exp_f32_e32 v89, v89
	v_pk_fma_f32 v[104:105], v[28:29], v[104:105], 0 op_sel_hi:[1,1,0]
	v_lshlrev_b32_e32 v28, 16, v94
	v_and_b32_e32 v29, 0xffff0000, v94
	v_add_f32_e32 v89, 1.0, v89
	v_rcp_f32_e32 v100, v89
	v_mul_f32_e32 v89, 0xbfb8aa3b, v93
	v_exp_f32_e32 v89, v89
	v_pk_fma_f32 v[104:105], v[24:25], v[28:29], v[104:105]
	v_lshlrev_b32_e32 v24, 16, v106
	v_and_b32_e32 v25, 0xffff0000, v106
	v_pk_fma_f32 v[96:97], v[96:97], v[24:25], v[104:105]
	v_lshlrev_b32_e32 v104, 16, v90
	v_and_b32_e32 v105, 0xffff0000, v90
	v_add_f32_e32 v89, 1.0, v89
	v_pk_fma_f32 v[0:1], v[0:1], v[104:105], v[96:97]
	v_rcp_f32_e32 v101, v89
	v_mul_f32_e32 v89, 0xbfb8aa3b, v0
	v_exp_f32_e32 v89, v89
	v_lshlrev_b32_e32 v102, 16, v103
	v_and_b32_e32 v103, 0xffff0000, v103
	v_pk_fma_f32 v[102:103], v[30:31], v[102:103], 0 op_sel_hi:[1,1,0]
	v_add_f32_e32 v89, 1.0, v89
	v_rcp_f32_e32 v96, v89
	v_mul_f32_e32 v89, 0xbfb8aa3b, v1
	v_exp_f32_e32 v89, v89
	v_lshlrev_b32_e32 v94, 16, v95
	v_and_b32_e32 v95, 0xffff0000, v95
	v_pk_fma_f32 v[94:95], v[26:27], v[94:95], v[102:103]
	v_lshlrev_b32_e32 v102, 16, v107
	v_and_b32_e32 v103, 0xffff0000, v107
	v_pk_fma_f32 v[94:95], v[98:99], v[102:103], v[94:95]
	v_lshlrev_b32_e32 v90, 16, v91
	v_and_b32_e32 v91, 0xffff0000, v91
	v_add_f32_e32 v89, 1.0, v89
	v_pk_fma_f32 v[2:3], v[2:3], v[90:91], v[94:95]
	v_rcp_f32_e32 v97, v89
	v_mul_f32_e32 v89, 0xbfb8aa3b, v2
	v_exp_f32_e32 v89, v89
	v_pk_mul_f32 v[32:33], v[32:33], v[34:35]
	v_pk_mul_f32 v[92:93], v[92:93], v[100:101]
	v_pk_mul_f32 v[34:35], v[32:33], v[32:33]
	v_add_f32_e32 v89, 1.0, v89
	v_rcp_f32_e32 v90, v89
	v_mul_f32_e32 v89, 0xbfb8aa3b, v3
	v_exp_f32_e32 v89, v89
	v_pk_mul_f32 v[100:101], v[92:93], v[92:93]
	v_pk_mul_f32 v[0:1], v[0:1], v[96:97]
	v_add_f32_e32 v89, 1.0, v89
	v_rcp_f32_e32 v91, v89
	v_add_f32_e32 v89, v34, v35
	v_add_f32_e32 v89, v100, v89
	v_pk_mul_f32 v[96:97], v[0:1], v[0:1]
	v_add_f32_e32 v89, v101, v89
	v_pk_mul_f32 v[2:3], v[2:3], v[90:91]
	v_add_f32_e32 v89, v96, v89
	v_pk_mul_f32 v[90:91], v[2:3], v[2:3]
	v_add_f32_e32 v89, v97, v89
	v_add_f32_e32 v89, v90, v89
	v_add_f32_e32 v89, v91, v89
	ds_bpermute_b32 v90, v37, v89
	s_waitcnt lgkmcnt(0)
	v_add_f32_e32 v89, v89, v90
	ds_bpermute_b32 v90, v38, v89
	s_waitcnt lgkmcnt(0)
	v_add_f32_e32 v89, v89, v90
	ds_bpermute_b32 v90, v39, v89
	s_waitcnt lgkmcnt(0)
	v_add_f32_e32 v89, v89, v90
	ds_bpermute_b32 v90, v40, v89
	s_and_saveexec_b64 s[22:23], vcc
	s_cbranch_execz .Ls1t3_754
	s_waitcnt lgkmcnt(0)
	v_add_f32_e32 v88, v89, v90
	v_add_f32_e32 v88, 0x358637bd, v88
	v_mul_f32_e32 v89, 0x4b800000, v88
	v_cmp_gt_f32_e32 vcc, s34, v88
	s_nop 1
	v_cndmask_b32_e32 v88, v88, v89, vcc
	v_rsq_f32_e32 v88, v88
	s_nop 0
	v_mul_f32_e32 v89, 0x45800000, v88
	v_cndmask_b32_e32 v88, v88, v89, vcc
	v_cmp_gt_u32_e32 vcc, s30, v111
	s_nop 1
	v_cndmask_b32_e32 v89, 1.0, v231, vcc
	v_mul_f32_e32 v88, v89, v88
.Ls1t3_754:
	s_or_b64 exec, exec, s[22:23]
	v_pk_mul_f32 v[0:1], v[0:1], v[88:89] op_sel_hi:[1,0]
	v_cmp_eq_u32_e32 vcc, 1, v109
	v_cvt_pk_bf16_f32 v96, v0, v1
	v_pk_mul_f32 v[0:1], v[2:3], v[88:89] op_sel_hi:[1,0]
	s_waitcnt lgkmcnt(0)
	v_pk_mul_f32 v[90:91], v[32:33], v[88:89] op_sel_hi:[1,0]
	v_cvt_pk_bf16_f32 v97, v0, v1
	v_cndmask_b32_e64 v0, v188, 0, vcc
	v_cmp_lt_u32_e32 vcc, s31, v111
	v_cvt_pk_bf16_f32 v94, v90, v91
	v_pk_mul_f32 v[90:91], v[92:93], v[88:89] op_sel_hi:[1,0]
	v_cndmask_b32_e32 v0, v232, v0, vcc
	v_add_u32_e32 v0, 0, v0
	v_mul_u32_u24_e32 v1, 0x110, v108
	v_cvt_pk_bf16_f32 v95, v90, v91
	v_add3_u32 v0, v0, v1, v151
	ds_write_b128 v0, v[94:97]
	v_add_u32_e32 v0, 0x400, v111
	v_lshrrev_b32_e32 v109, 10, v0
	v_add_u32_e32 v0, 0x60, v218
	v_and_b32_e32 v108, 63, v0
	v_lshl_add_u32 v1, v109, 9, v36
	v_add_u32_e32 v0, s86, v108
	v_mov_b32_e32 v92, 0
	v_cmp_lt_i32_e32 vcc, -1, v0
	v_lshlrev_b32_e32 v56, 1, v1
	v_mov_b32_e32 v100, 0
	v_mov_b32_e32 v101, 0
	v_mov_b32_e32 v102, 0
	v_mov_b32_e32 v103, 0
	s_and_saveexec_b64 s[22:23], vcc
	v_add_u32_e32 v1, s41, v0
	v_mov_b64_e32 v[2:3], s[10:11]
	v_mad_u64_u32 v[2:3], vcc, v1, s25, v[2:3]
	v_lshl_add_u64 v[2:3], v[2:3], 0, v[56:57]
	global_load_dwordx4 v[100:103], v[2:3], off

; #define LAS __attribute__((address_space(3)))
; __device__ __forceinline__ float lo_bf(unsigned w) { return __uint_as_float(w << 16); }
; __device__ __forceinline__ float hi_bf(unsigned w) { return __uint_as_float(w & 0xffff0000u); }
; __device__ __forceinline__ unsigned pk2(float lo, float hi) { const f32x2_t v = {lo, hi}; const bf16x2_t b = __builtin_convertvector(v, bf16x2_t); return __builtin_bit_cast(unsigned, b); }
; __device__ __forceinline__ float silu_(float x) { return x * sigm(x); }
; __device__ __forceinline__ void dn_prep_item(const Args& a, LAS unsigned char* lds, int item, int tid, int wave, int lane, int& cwh, int next_item) {
;     ...
;     for (int r = 0; r < 6; ++r) { const int task = tid + NTHR * r, which = task >> 10, i = (task & 1023) >> 4, gq = task & 15;
;         const int col = 1024 + which * 512 + h * 128 + 8 * gq;
;         v4u xv[4];
; #pragma unroll
;         for (int jj = 0; jj < 4; ++jj) { const int pos = n * 64 + i - 3 + jj; xv[jj] = (v4u){0u, 0u, 0u, 0u};
;             if (pos >= 0) xv[jj] = *(const v4u*)(P + (size_t)(b * T + pos) * NIN + col); }
;         float o[8];
; #pragma unroll
;         for (int q = 0; q < 8; ++q) o[q] = 0.f;
; #pragma unroll
;         for (int jj = 0; jj < 4; ++jj) { const v4u v = xv[jj];
;             const f32x4 w0 = *(const LAS f32x4*)(cwl + (which * 4 + jj) * 128 + 8 * gq), w1 = *(const LAS f32x4*)(cwl + (which * 4 + jj) * 128 + 8 * gq + 4);
;             o[0] += w0[0] * lo_bf(v.x); o[1] += w0[1] * hi_bf(v.x); o[2] += w0[2] * lo_bf(v.y); o[3] += w0[3] * hi_bf(v.y);
;             o[4] += w1[0] * lo_bf(v.z); o[5] += w1[1] * hi_bf(v.z); o[6] += w1[2] * lo_bf(v.w); o[7] += w1[3] * hi_bf(v.w); }
;         float s = 0.f;
; #pragma unroll
;         for (int q = 0; q < 8; ++q) { o[q] = silu_(o[q]); s += o[q] * o[q]; }
;         s += __shfl_xor(s, 1); s += __shfl_xor(s, 2); s += __shfl_xor(s, 4); s += __shfl_xor(s, 8);
;         const float inv = which == 2 ? 1.0f : rsqrtf(s + EPS) * (which == 0 ? 0.08838834764831845f : 1.0f);
;         v4u w; w.x = pk2(o[0] * inv, o[1] * inv); w.y = pk2(o[2] * inv, o[3] * inv); w.z = pk2(o[4] * inv, o[5] * inv); w.w = pk2(o[6] * inv, o[7] * inv);
;         *(LAS v4u*)(lds + (which == 0 ? L_QS : which == 1 ? L_KH : L_V) + i * KS_ + 16 * gq) = w;
.Ls1t5_768:
	s_or_b64 exec, exec, s[22:23]
	v_or_b32_e32 v2, s39, v108
	v_mov_b64_e32 v[0:1], s[10:11]
	v_mad_u64_u32 v[0:1], s[22:23], v2, s25, v[0:1]
	v_lshl_add_u64 v[0:1], v[0:1], 0, v[56:57]
	global_load_dwordx4 v[88:91], v[0:1], off
	v_lshl_add_u32 v0, v114, 11, v150
	ds_read_b128 v[72:75], v0
	ds_read_b128 v[28:31], v0 offset:16
	ds_read_b128 v[76:79], v0 offset:512
	ds_read_b128 v[24:27], v0 offset:528
	ds_read_b128 v[80:83], v0 offset:1024
	ds_read_b128 v[12:15], v0 offset:1040
	ds_read_b128 v[84:87], v0 offset:1536
	ds_read_b128 v[0:3], v0 offset:1552
	s_waitcnt vmcnt(7)
	v_lshlrev_b32_e32 v32, 16, v16
	v_and_b32_e32 v33, 0xffff0000, v16
	s_waitcnt lgkmcnt(7)
	v_pk_fma_f32 v[32:33], v[72:73], v[32:33], 0 op_sel_hi:[1,1,0]
	s_waitcnt vmcnt(6)
	v_lshlrev_b32_e32 v34, 16, v8
	v_and_b32_e32 v35, 0xffff0000, v8
	s_waitcnt lgkmcnt(5)
	v_pk_fma_f32 v[32:33], v[76:77], v[34:35], v[32:33]
	s_waitcnt vmcnt(5)
	v_lshlrev_b32_e32 v34, 16, v20
	v_and_b32_e32 v35, 0xffff0000, v20
	s_waitcnt lgkmcnt(3)
	v_pk_fma_f32 v[32:33], v[80:81], v[34:35], v[32:33]
	v_lshlrev_b32_e32 v16, 16, v17
	v_and_b32_e32 v17, 0xffff0000, v17
	v_pk_fma_f32 v[16:17], v[74:75], v[16:17], 0 op_sel_hi:[1,1,0]
	v_lshlrev_b32_e32 v20, 16, v18
	v_cmp_ne_u32_e32 vcc, 2, v114
	s_waitcnt vmcnt(4)
	v_lshlrev_b32_e32 v34, 16, v4
	v_and_b32_e32 v35, 0xffff0000, v4
	s_waitcnt lgkmcnt(1)
	v_pk_fma_f32 v[32:33], v[84:85], v[34:35], v[32:33]
	s_nop 0
	v_mul_f32_e32 v4, 0xbfb8aa3b, v32
	v_exp_f32_e32 v8, v4
	v_mov_b32_e32 v4, 1.0
	v_add_f32_e32 v8, 1.0, v8
	v_rcp_f32_e32 v34, v8
	v_mul_f32_e32 v8, 0xbfb8aa3b, v33
	v_exp_f32_e32 v8, v8
	s_nop 0
	v_add_f32_e32 v8, 1.0, v8
	v_rcp_f32_e32 v35, v8
	v_lshlrev_b32_e32 v8, 16, v9
	v_and_b32_e32 v9, 0xffff0000, v9
	v_pk_fma_f32 v[8:9], v[78:79], v[8:9], v[16:17]
	v_lshlrev_b32_e32 v16, 16, v21
	v_and_b32_e32 v17, 0xffff0000, v21
	v_pk_fma_f32 v[8:9], v[82:83], v[16:17], v[8:9]
	v_lshlrev_b32_e32 v16, 16, v5
	v_and_b32_e32 v17, 0xffff0000, v5
	v_pk_fma_f32 v[8:9], v[86:87], v[16:17], v[8:9]
	v_and_b32_e32 v21, 0xffff0000, v18
	v_mul_f32_e32 v5, 0xbfb8aa3b, v8
	v_exp_f32_e32 v5, v5
	v_pk_fma_f32 v[20:21], v[28:29], v[20:21], 0 op_sel_hi:[1,1,0]
	v_lshlrev_b32_e32 v28, 16, v10
	v_and_b32_e32 v29, 0xffff0000, v10
	v_add_f32_e32 v5, 1.0, v5
	v_rcp_f32_e32 v16, v5
	v_mul_f32_e32 v5, 0xbfb8aa3b, v9
	v_exp_f32_e32 v5, v5
	v_pk_fma_f32 v[20:21], v[24:25], v[28:29], v[20:21]
	v_lshlrev_b32_e32 v24, 16, v22
	v_and_b32_e32 v25, 0xffff0000, v22
	v_pk_fma_f32 v[12:13], v[12:13], v[24:25], v[20:21]
	v_lshlrev_b32_e32 v20, 16, v6
	v_and_b32_e32 v21, 0xffff0000, v6
	v_add_f32_e32 v5, 1.0, v5
	s_waitcnt lgkmcnt(0)
	v_pk_fma_f32 v[0:1], v[0:1], v[20:21], v[12:13]
	v_rcp_f32_e32 v17, v5
	v_mul_f32_e32 v5, 0xbfb8aa3b, v0
	v_exp_f32_e32 v5, v5
	v_lshlrev_b32_e32 v18, 16, v19
	v_and_b32_e32 v19, 0xffff0000, v19
	v_pk_fma_f32 v[18:19], v[30:31], v[18:19], 0 op_sel_hi:[1,1,0]
	v_add_f32_e32 v5, 1.0, v5
	v_rcp_f32_e32 v12, v5
	v_mul_f32_e32 v5, 0xbfb8aa3b, v1
	v_exp_f32_e32 v5, v5
	v_lshlrev_b32_e32 v10, 16, v11
	v_and_b32_e32 v11, 0xffff0000, v11
	v_pk_fma_f32 v[10:11], v[26:27], v[10:11], v[18:19]
	v_lshlrev_b32_e32 v18, 16, v23
	v_and_b32_e32 v19, 0xffff0000, v23
	v_pk_fma_f32 v[10:11], v[14:15], v[18:19], v[10:11]
	v_lshlrev_b32_e32 v6, 16, v7
	v_and_b32_e32 v7, 0xffff0000, v7
	v_add_f32_e32 v5, 1.0, v5
	v_pk_fma_f32 v[2:3], v[2:3], v[6:7], v[10:11]
	v_rcp_f32_e32 v13, v5
	v_mul_f32_e32 v5, 0xbfb8aa3b, v2
	v_exp_f32_e32 v5, v5
	v_pk_mul_f32 v[32:33], v[32:33], v[34:35]
	v_pk_mul_f32 v[8:9], v[8:9], v[16:17]
	v_pk_mul_f32 v[34:35], v[32:33], v[32:33]
	v_add_f32_e32 v5, 1.0, v5
	v_rcp_f32_e32 v6, v5
	v_mul_f32_e32 v5, 0xbfb8aa3b, v3
	v_exp_f32_e32 v5, v5
	v_pk_mul_f32 v[16:17], v[8:9], v[8:9]
	v_pk_mul_f32 v[0:1], v[0:1], v[12:13]
	v_add_f32_e32 v5, 1.0, v5
	v_rcp_f32_e32 v7, v5
	v_add_f32_e32 v5, v34, v35
	v_add_f32_e32 v5, v16, v5
	v_pk_mul_f32 v[12:13], v[0:1], v[0:1]
	v_add_f32_e32 v5, v17, v5
	v_pk_mul_f32 v[2:3], v[2:3], v[6:7]
	v_add_f32_e32 v5, v12, v5
	v_pk_mul_f32 v[6:7], v[2:3], v[2:3]
	v_add_f32_e32 v5, v13, v5
	v_add_f32_e32 v5, v6, v5
	v_add_f32_e32 v5, v7, v5
	ds_bpermute_b32 v6, v37, v5
	s_waitcnt lgkmcnt(0)
	v_add_f32_e32 v5, v5, v6
	ds_bpermute_b32 v6, v38, v5
	s_waitcnt lgkmcnt(0)
	v_add_f32_e32 v5, v5, v6
	ds_bpermute_b32 v6, v39, v5
	s_waitcnt lgkmcnt(0)
	v_add_f32_e32 v5, v5, v6
	ds_bpermute_b32 v6, v40, v5
	s_and_saveexec_b64 s[22:23], vcc
	s_cbranch_execz .Ls1t4_762
	s_waitcnt lgkmcnt(0)
	v_add_f32_e32 v4, v5, v6
	v_add_f32_e32 v4, 0x358637bd, v4
	v_mul_f32_e32 v5, 0x4b800000, v4
	v_cmp_gt_f32_e32 vcc, s34, v4
	s_nop 1
	v_cndmask_b32_e32 v4, v4, v5, vcc
	v_rsq_f32_e32 v4, v4
	s_nop 0
	v_mul_f32_e32 v5, 0x45800000, v4
	v_cndmask_b32_e32 v4, v4, v5, vcc
	v_cmp_gt_u32_e32 vcc, s30, v112
	s_nop 1
	v_cndmask_b32_e32 v5, 1.0, v231, vcc
	v_mul_f32_e32 v4, v5, v4
; #define LAS __attribute__((address_space(3)))
; __device__ __forceinline__ float lo_bf(unsigned w) { return __uint_as_float(w << 16); }
; __device__ __forceinline__ float hi_bf(unsigned w) { return __uint_as_float(w & 0xffff0000u); }
; __device__ __forceinline__ unsigned pk2(float lo, float hi) { const f32x2_t v = {lo, hi}; const bf16x2_t b = __builtin_convertvector(v, bf16x2_t); return __builtin_bit_cast(unsigned, b); }
; __device__ __forceinline__ float silu_(float x) { return x * sigm(x); }
; __device__ __forceinline__ void dn_prep_item(const Args& a, LAS unsigned char* lds, int item, int tid, int wave, int lane, int& cwh, int next_item) {
;     ...
;     for (int r = 0; r < 6; ++r) { const int task = tid + NTHR * r, which = task >> 10, i = (task & 1023) >> 4, gq = task & 15;
;         const int col = 1024 + which * 512 + h * 128 + 8 * gq;
;         v4u xv[4];
; #pragma unroll
;         for (int jj = 0; jj < 4; ++jj) { const int pos = n * 64 + i - 3 + jj; xv[jj] = (v4u){0u, 0u, 0u, 0u};
;             if (pos >= 0) xv[jj] = *(const v4u*)(P + (size_t)(b * T + pos) * NIN + col); }
;         float o[8];
; #pragma unroll
;         for (int q = 0; q < 8; ++q) o[q] = 0.f;
; #pragma unroll
;         for (int jj = 0; jj < 4; ++jj) { const v4u v = xv[jj];
;             const f32x4 w0 = *(const LAS f32x4*)(cwl + (which * 4 + jj) * 128 + 8 * gq), w1 = *(const LAS f32x4*)(cwl + (which * 4 + jj) * 128 + 8 * gq + 4);
;             o[0] += w0[0] * lo_bf(v.x); o[1] += w0[1] * hi_bf(v.x); o[2] += w0[2] * lo_bf(v.y); o[3] += w0[3] * hi_bf(v.y);
;             o[4] += w1[0] * lo_bf(v.z); o[5] += w1[1] * hi_bf(v.z); o[6] += w1[2] * lo_bf(v.w); o[7] += w1[3] * hi_bf(v.w); }
;         float s = 0.f;
; #pragma unroll
;         for (int q = 0; q < 8; ++q) { o[q] = silu_(o[q]); s += o[q] * o[q]; }
;         s += __shfl_xor(s, 1); s += __shfl_xor(s, 2); s += __shfl_xor(s, 4); s += __shfl_xor(s, 8);
;         const float inv = which == 2 ? 1.0f : rsqrtf(s + EPS) * (which == 0 ? 0.08838834764831845f : 1.0f);
;         v4u w; w.x = pk2(o[0] * inv, o[1] * inv); w.y = pk2(o[2] * inv, o[3] * inv); w.z = pk2(o[4] * inv, o[5] * inv); w.w = pk2(o[6] * inv, o[7] * inv);
;         *(LAS v4u*)(lds + (which == 0 ? L_QS : which == 1 ? L_KH : L_V) + i * KS_ + 16 * gq) = w;
.Ls1t4_762:
	s_or_b64 exec, exec, s[22:23]
	v_pk_mul_f32 v[0:1], v[0:1], v[4:5] op_sel_hi:[1,0]
	v_cmp_eq_u32_e32 vcc, 1, v114
	v_cvt_pk_bf16_f32 v12, v0, v1
	v_pk_mul_f32 v[0:1], v[2:3], v[4:5] op_sel_hi:[1,0]
	s_waitcnt lgkmcnt(0)
	v_pk_mul_f32 v[6:7], v[32:33], v[4:5] op_sel_hi:[1,0]
	v_cvt_pk_bf16_f32 v13, v0, v1
	v_cndmask_b32_e64 v0, v188, 0, vcc
	v_cmp_lt_u32_e32 vcc, s31, v112
	v_cvt_pk_bf16_f32 v10, v6, v7
	v_pk_mul_f32 v[6:7], v[8:9], v[4:5] op_sel_hi:[1,0]
	v_cndmask_b32_e32 v0, v232, v0, vcc
	v_add_u32_e32 v0, 0, v0
	v_mul_u32_u24_e32 v1, 0x110, v113
	v_cvt_pk_bf16_f32 v11, v6, v7
	v_add3_u32 v0, v0, v1, v151
	ds_write_b128 v0, v[10:13]
	v_lshl_add_u32 v0, v109, 11, v150
	ds_read_b128 v[44:47], v0
	ds_read_b128 v[28:31], v0 offset:16
	ds_read_b128 v[72:75], v0 offset:512
	ds_read_b128 v[24:27], v0 offset:528
	ds_read_b128 v[76:79], v0 offset:1024
	ds_read_b128 v[96:99], v0 offset:1040
	ds_read_b128 v[80:83], v0 offset:1536
	ds_read_b128 v[0:3], v0 offset:1552
	s_waitcnt vmcnt(3)
	v_lshlrev_b32_e32 v32, 16, v100
	v_and_b32_e32 v33, 0xffff0000, v100
	s_waitcnt lgkmcnt(7)
	v_pk_fma_f32 v[32:33], v[44:45], v[32:33], 0 op_sel_hi:[1,1,0]
	s_waitcnt vmcnt(2)
	v_lshlrev_b32_e32 v34, 16, v92
	v_and_b32_e32 v35, 0xffff0000, v92
	s_waitcnt lgkmcnt(5)
	v_pk_fma_f32 v[32:33], v[72:73], v[34:35], v[32:33]
	s_waitcnt vmcnt(1)
	v_lshlrev_b32_e32 v34, 16, v104
	v_and_b32_e32 v35, 0xffff0000, v104
	s_waitcnt lgkmcnt(3)
	v_pk_fma_f32 v[32:33], v[76:77], v[34:35], v[32:33]
	v_lshlrev_b32_e32 v100, 16, v101
	v_and_b32_e32 v101, 0xffff0000, v101
	v_pk_fma_f32 v[100:101], v[46:47], v[100:101], 0 op_sel_hi:[1,1,0]
	v_lshlrev_b32_e32 v104, 16, v102
	v_cmp_ne_u32_e32 vcc, 2, v109
	s_waitcnt vmcnt(0)
	v_lshlrev_b32_e32 v34, 16, v88
	v_and_b32_e32 v35, 0xffff0000, v88
	s_waitcnt lgkmcnt(1)
	v_pk_fma_f32 v[32:33], v[80:81], v[34:35], v[32:33]
	s_nop 0
	v_mul_f32_e32 v88, 0xbfb8aa3b, v32
	v_exp_f32_e32 v92, v88
	v_mov_b32_e32 v88, 1.0
	v_add_f32_e32 v92, 1.0, v92
	v_rcp_f32_e32 v34, v92
	v_mul_f32_e32 v92, 0xbfb8aa3b, v33
	v_exp_f32_e32 v92, v92
	s_nop 0
	v_add_f32_e32 v92, 1.0, v92
	v_rcp_f32_e32 v35, v92
	v_lshlrev_b32_e32 v92, 16, v93
	v_and_b32_e32 v93, 0xffff0000, v93
	v_pk_fma_f32 v[92:93], v[74:75], v[92:93], v[100:101]
	v_lshlrev_b32_e32 v100, 16, v105
	v_and_b32_e32 v101, 0xffff0000, v105
	v_pk_fma_f32 v[92:93], v[78:79], v[100:101], v[92:93]
	v_lshlrev_b32_e32 v100, 16, v89
	v_and_b32_e32 v101, 0xffff0000, v89
	v_pk_fma_f32 v[92:93], v[82:83], v[100:101], v[92:93]
	v_and_b32_e32 v105, 0xffff0000, v102
	v_mul_f32_e32 v89, 0xbfb8aa3b, v92
	v_exp_f32_e32 v89, v89
	v_pk_fma_f32 v[104:105], v[28:29], v[104:105], 0 op_sel_hi:[1,1,0]
	v_lshlrev_b32_e32 v28, 16, v94
	v_and_b32_e32 v29, 0xffff0000, v94
	v_add_f32_e32 v89, 1.0, v89
	v_rcp_f32_e32 v100, v89
	v_mul_f32_e32 v89, 0xbfb8aa3b, v93
	v_exp_f32_e32 v89, v89
	v_pk_fma_f32 v[104:105], v[24:25], v[28:29], v[104:105]
	v_lshlrev_b32_e32 v24, 16, v106
	v_and_b32_e32 v25, 0xffff0000, v106
	v_pk_fma_f32 v[96:97], v[96:97], v[24:25], v[104:105]
	v_lshlrev_b32_e32 v104, 16, v90
	v_and_b32_e32 v105, 0xffff0000, v90
	v_add_f32_e32 v89, 1.0, v89
	s_waitcnt lgkmcnt(0)
	v_pk_fma_f32 v[0:1], v[0:1], v[104:105], v[96:97]
	v_rcp_f32_e32 v101, v89
	v_mul_f32_e32 v89, 0xbfb8aa3b, v0
	v_exp_f32_e32 v89, v89
	v_lshlrev_b32_e32 v102, 16, v103
	v_and_b32_e32 v103, 0xffff0000, v103
	v_pk_fma_f32 v[102:103], v[30:31], v[102:103], 0 op_sel_hi:[1,1,0]
	v_add_f32_e32 v89, 1.0, v89
	v_rcp_f32_e32 v96, v89
	v_mul_f32_e32 v89, 0xbfb8aa3b, v1
	v_exp_f32_e32 v89, v89
	v_lshlrev_b32_e32 v94, 16, v95
	v_and_b32_e32 v95, 0xffff0000, v95
	v_pk_fma_f32 v[94:95], v[26:27], v[94:95], v[102:103]
	v_lshlrev_b32_e32 v102, 16, v107
	v_and_b32_e32 v103, 0xffff0000, v107
	v_pk_fma_f32 v[94:95], v[98:99], v[102:103], v[94:95]
	v_lshlrev_b32_e32 v90, 16, v91
	v_and_b32_e32 v91, 0xffff0000, v91
	v_add_f32_e32 v89, 1.0, v89
	v_pk_fma_f32 v[2:3], v[2:3], v[90:91], v[94:95]
	v_rcp_f32_e32 v97, v89
	v_mul_f32_e32 v89, 0xbfb8aa3b, v2
	v_exp_f32_e32 v89, v89
	v_pk_mul_f32 v[32:33], v[32:33], v[34:35]
	v_pk_mul_f32 v[92:93], v[92:93], v[100:101]
	v_pk_mul_f32 v[34:35], v[32:33], v[32:33]
	v_add_f32_e32 v89, 1.0, v89
	v_rcp_f32_e32 v90, v89
	v_mul_f32_e32 v89, 0xbfb8aa3b, v3
	v_exp_f32_e32 v89, v89
	v_pk_mul_f32 v[100:101], v[92:93], v[92:93]
	v_pk_mul_f32 v[0:1], v[0:1], v[96:97]
	v_add_f32_e32 v89, 1.0, v89
	v_rcp_f32_e32 v91, v89
	v_add_f32_e32 v89, v34, v35
	v_add_f32_e32 v89, v100, v89
	v_pk_mul_f32 v[96:97], v[0:1], v[0:1]
	v_add_f32_e32 v89, v101, v89
	v_pk_mul_f32 v[2:3], v[2:3], v[90:91]
	v_add_f32_e32 v89, v96, v89
	v_pk_mul_f32 v[90:91], v[2:3], v[2:3]
	v_add_f32_e32 v89, v97, v89
	v_add_f32_e32 v89, v90, v89
	v_add_f32_e32 v89, v91, v89
	ds_bpermute_b32 v90, v37, v89
	s_waitcnt lgkmcnt(0)
	v_add_f32_e32 v89, v89, v90
	ds_bpermute_b32 v90, v38, v89
	s_waitcnt lgkmcnt(0)
	v_add_f32_e32 v89, v89, v90
	ds_bpermute_b32 v90, v39, v89
	s_waitcnt lgkmcnt(0)
	v_add_f32_e32 v89, v89, v90
	ds_bpermute_b32 v90, v40, v89
	s_and_saveexec_b64 s[22:23], vcc
	s_cbranch_execz .Ls1t5_745
	s_waitcnt lgkmcnt(0)
	v_add_f32_e32 v88, v89, v90
	v_add_f32_e32 v88, 0x358637bd, v88
	v_mul_f32_e32 v89, 0x4b800000, v88
	v_cmp_gt_f32_e32 vcc, s34, v88
	s_nop 1
	v_cndmask_b32_e32 v88, v88, v89, vcc
	v_rsq_f32_e32 v88, v88
	s_nop 0
	v_mul_f32_e32 v89, 0x45800000, v88
	v_cndmask_b32_e32 v88, v88, v89, vcc
.Ls1t5_745:
	s_or_b64 exec, exec, s[22:23]
	s_waitcnt lgkmcnt(0)
	v_pk_mul_f32 v[90:91], v[32:33], v[88:89] op_sel_hi:[1,0]
	v_pk_mul_f32 v[92:93], v[92:93], v[88:89] op_sel_hi:[1,0]
	v_pk_mul_f32 v[0:1], v[0:1], v[88:89] op_sel_hi:[1,0]
	v_cvt_pk_bf16_f32 v90, v90, v91
	v_cvt_pk_bf16_f32 v91, v92, v93
	v_cvt_pk_bf16_f32 v92, v0, v1
	v_pk_mul_f32 v[0:1], v[2:3], v[88:89] op_sel_hi:[1,0]
	v_cmp_eq_u32_e32 vcc, 1, v109
	v_cvt_pk_bf16_f32 v93, v0, v1
	v_mul_u32_u24_e32 v1, 0x110, v108
	v_cndmask_b32_e64 v0, v188, 0, vcc
	v_add_u32_e32 v0, 0, v0
	v_add3_u32 v0, v0, v1, v151
	ds_write_b128 v0, v[90:93]
